# v15 plus HGRN2 scan MFMA stages: all LDS fragment reads issued up front into free VGPRs with counted lgkmcnt waits (was read-wait-mfma per step)
# speedup vs baseline: 1.0024x; 1.0010x over previous
; #define LAS __attribute__((address_space(3)))
; #define MFMA32(a, b, c) __builtin_amdgcn_mfma_f32_32x32x16_bf16((a), (b), (c), 0, 0, 0)
; __device__ __forceinline__ unsigned pk2(float lo, float hi) { f32x2_t v = {lo, hi}; bf16x2_t b = __builtin_convertvector(v, bf16x2_t); return __builtin_bit_cast(unsigned, b); }
; __device__ __forceinline__ void scan_item(const Ctx& C, int b, int h, int half, const bf16* HQ, const bf16* LOGF, bf16* HI  , float* SSQ) {
;     ...
;         { const LAS float* gp = (const LAS float*)(L + O_G) + 32 * kt_own + 4 * hh;
; #pragma unroll
;           for (int g = 0; g < 4; ++g) { const f32x4 gv = *(const LAS f32x4*)(gp + 8 * g);
; #pragma unroll
;               for (int e = 0; e < 4; ++e) sacc[4 * g + e] *= gv[e]; }
; #pragma unroll
;           for (int s = 0; s < 4; ++s) { const bf16x8 a = *(const LAS bf16x8*)(L + O_KDT + ((32 * kt_own + r) * P64 + 16 * s + 8 * hh) * 2), bb = *(const LAS bf16x8*)(L + O_VT + ((32 * di_own + r) * P64 + 16 * s + 8 * hh) * 2); sacc = MFMA32(a, bb, sacc); }
; #pragma unroll
;           for (int g = 0; g < 4; ++g) *(LAS v2u*)(L + O_ST + ((32 * di_own + r) * P128 + 32 * kt_own + 8 * g + 4 * hh) * 2) = (v2u){pk2(sacc[4 * g], sacc[4 * g + 1]), pk2(sacc[4 * g + 2], sacc[4 * g + 3])}; }
;         __syncthreads();
.LBB0_707:
	ds_read_b128 v[2:5], v112
	ds_read_b128 v[6:9], v112 offset:32
	ds_read_b128 v[10:13], v112 offset:64
	s_nop 1
	ds_read_b128 v[32:35], v112 offset:96
	s_add_i32 s58, s58, 1
	s_waitcnt lgkmcnt(3)
	v_pk_mul_f32 v[18:19], v[18:19], v[4:5]
	s_waitcnt lgkmcnt(2)
	v_pk_mul_f32 v[22:23], v[22:23], v[8:9]
	s_waitcnt lgkmcnt(1)
	v_pk_mul_f32 v[26:27], v[26:27], v[12:13]
	s_waitcnt lgkmcnt(0)
	v_pk_mul_f32 v[30:31], v[30:31], v[34:35]
	v_pk_mul_f32 v[28:29], v[28:29], v[32:33]
	v_pk_mul_f32 v[24:25], v[24:25], v[10:11]
	v_pk_mul_f32 v[20:21], v[20:21], v[6:7]
	v_pk_mul_f32 v[16:17], v[16:17], v[2:3]
	ds_read_b128 v[2:5], v144
	ds_read_b128 v[6:9], v144 offset:32
	ds_read_b128 v[10:13], v1
	ds_read_b128 v[32:35], v1 offset:32
	ds_read_b128 v[166:169], v144 offset:64
	ds_read_b128 v[170:173], v1 offset:64
	ds_read_b128 v[174:177], v144 offset:96
	ds_read_b128 v[178:181], v1 offset:96
	s_waitcnt lgkmcnt(5)
	v_mfma_f32_32x32x16_bf16 v[16:31], v[2:5], v[10:13], v[16:31]
	s_add_u32 s72, s72, 0x40000
	s_addc_u32 s73, s73, 0
	s_cmp_eq_u32 s72, 0x800000
	s_waitcnt lgkmcnt(4)
	v_mfma_f32_32x32x16_bf16 v[16:31], v[6:9], v[32:35], v[16:31]
	s_waitcnt lgkmcnt(2)
	v_mfma_f32_32x32x16_bf16 v[16:31], v[166:169], v[170:173], v[16:31]
	v_add_u32_e32 v1, 0xc800, v145
	s_waitcnt lgkmcnt(0)
	v_mfma_f32_32x32x16_bf16 v[16:31], v[174:177], v[178:181], v[16:31]
	s_nop 11
	v_cvt_pk_bf16_f32 v2, v16, v17
	v_cvt_pk_bf16_f32 v3, v18, v19
	v_cvt_pk_bf16_f32 v4, v20, v21
	v_cvt_pk_bf16_f32 v5, v22, v23
	ds_write2_b64 v1, v[2:3], v[4:5] offset0:128 offset1:130
	v_cvt_pk_bf16_f32 v2, v24, v25
	v_cvt_pk_bf16_f32 v3, v26, v27
	v_cvt_pk_bf16_f32 v4, v28, v29
	v_cvt_pk_bf16_f32 v5, v30, v31
	ds_write2_b64 v1, v[2:3], v[4:5] offset0:132 offset1:134
	s_waitcnt lgkmcnt(0)
	s_barrier
	s_cbranch_scc1 .LBB0_725

; #define LAS __attribute__((address_space(3)))
; __device__ __forceinline__ float bflo(unsigned u) { return __uint_as_float(u << 16); }
; __device__ __forceinline__ void scan_item(const Ctx& C, int b, int h, int half, const bf16* HQ, const bf16* LOGF, bf16* HI  , float* SSQ) {
;     ...
;           for (int i = 0; i < 8; ++i) { const int t = 8 * w + i; const unsigned lw = *(const LAS unsigned*)(L + O_RL + (t * P128 + k0) * 2); const unsigned qq = *(const LAS unsigned*)(L + O_RQ + (t * P128 + k0) * 2);
;               const float l0 = bflo(lw) * 1.4426950408889634f, l1 = bfhi(lw) * 1.4426950408889634f; q0[i] = bflo(qq); q1[i] = bfhi(qq); r0 += l0; r1 += l1; c0[i] = r0; c1[i] = r1;
;               kk0[i] = 1.0f - __builtin_amdgcn_exp2f(l0); kk1[i] = 1.0f - __builtin_amdgcn_exp2f(l1); }
;           *(LAS f32x2_t*)(L + O_SEG + (w * 128 + k0) * 4) = (f32x2_t){r0, r1}; }
;         __syncthreads();
;         { float pre0 = 0.f, pre1 = 0.f, mid0 = 0.f, mid1 = 0.f, tot0 = 0.f, tot1 = 0.f;
; #pragma unroll
;           for (int s8 = 0; s8 < 8; ++s8) { const f32x2_t sv = *(const LAS f32x2_t*)(L + O_SEG + (s8 * 128 + k0) * 4); if (s8 < w) { pre0 += sv.x; pre1 += sv.y; } if (s8 < 4) { mid0 += sv.x; mid1 += sv.y; } tot0 += sv.x; tot1 += sv.y; }
;           if (w == 0) *(LAS f32x2_t*)(L + O_G + k0 * 4) = (f32x2_t){__builtin_amdgcn_exp2f(tot0), __builtin_amdgcn_exp2f(tot1)};
;           const float cm0 = __builtin_amdgcn_exp2f(fminf(-mid0, 115.f)), cm1 = __builtin_amdgcn_exp2f(fminf(-mid1, 115.f));
;           float kd0[8], kd1[8];
; #pragma unroll
;           for (int i = 0; i < 8; ++i) { const int t = 8 * w + i; const float b0 = pre0 + c0[i], b1 = pre1 + c1[i];
;               const float e0 = __builtin_amdgcn_exp2f(b0), e1 = __builtin_amdgcn_exp2f(b1);
;               const float qd0 = q0[i] * e0, qd1 = q1[i] * e1, qt0 = qd0 * cm0, qt1 = qd1 * cm1;
;               const float kt0 = kk0[i] * __builtin_amdgcn_exp2f(fminf(mid0 - b0, 115.f)), kt1 = kk1[i] * __builtin_amdgcn_exp2f(fminf(mid1 - b1, 115.f));
;               kd0[i] = kk0[i] * __builtin_amdgcn_exp2f(tot0 - b0); kd1[i] = kk1[i] * __builtin_amdgcn_exp2f(tot1 - b1);
;               *(LAS unsigned*)(L + O_QD + (t * P128 + k0) * 2) = pk2(qd0, qd1); *(LAS unsigned*)(L + O_QT + (t * P128 + k0) * 2) = pk2(qt0, qt1); *(LAS unsigned*)(L + O_KT + (t * P128 + k0) * 2) = pk2(kt0, kt1); }
.LBB0_716:
	v_pk_mul_f32 v[6:7], v[92:93], s[0:1] op_sel_hi:[1,0]
	v_lshlrev_b32_e32 v156, 16, v42
	v_exp_f32_e32 v92, v6
	v_exp_f32_e32 v93, v7
	v_pk_mul_f32 v[6:7], v[96:97], s[0:1] op_sel_hi:[1,0]
	v_and_b32_e32 v157, 0xffff0000, v42
	v_exp_f32_e32 v96, v6
	v_exp_f32_e32 v97, v7
	v_pk_mul_f32 v[6:7], v[94:95], s[0:1] op_sel_hi:[1,0]
	v_lshlrev_b32_e32 v158, 16, v43
	v_exp_f32_e32 v94, v6
	v_exp_f32_e32 v95, v7
	v_pk_mul_f32 v[6:7], v[98:99], s[0:1] op_sel_hi:[1,0]
	v_and_b32_e32 v159, 0xffff0000, v43
	v_exp_f32_e32 v98, v6
	v_exp_f32_e32 v99, v7
	v_pk_mul_f32 v[6:7], v[100:101], s[0:1] op_sel_hi:[1,0]
	v_lshlrev_b32_e32 v160, 16, v44
	v_exp_f32_e32 v100, v6
	v_exp_f32_e32 v101, v7
	v_pk_mul_f32 v[6:7], v[106:107], s[0:1] op_sel_hi:[1,0]
	v_and_b32_e32 v161, 0xffff0000, v44
	v_exp_f32_e32 v106, v6
	v_exp_f32_e32 v107, v7
	v_pk_mul_f32 v[6:7], v[104:105], s[0:1] op_sel_hi:[1,0]
	v_lshlrev_b32_e32 v162, 16, v45
	v_exp_f32_e32 v104, v6
	v_exp_f32_e32 v105, v7
	v_pk_mul_f32 v[6:7], v[102:103], s[0:1] op_sel_hi:[1,0]
	v_and_b32_e32 v163, 0xffff0000, v45
	v_exp_f32_e32 v102, v6
	v_pk_add_f32 v[42:43], v[104:105], 1.0 op_sel_hi:[1,0] neg_lo:[1,0] neg_hi:[1,0]
	v_cndmask_b32_e64 v105, 0, v154, s[8:9]
	v_cndmask_b32_e64 v104, 0, v155, s[8:9]
	v_add_f32_e32 v8, v8, v105
	v_add_f32_e32 v9, v9, v104
	v_cndmask_b32_e64 v8, v105, v8, s[10:11]
	v_cndmask_b32_e64 v9, v104, v9, s[10:11]
	v_add_f32_e32 v2, v2, v8
	v_add_f32_e32 v3, v3, v9
	v_cndmask_b32_e64 v2, v8, v2, s[12:13]
	v_cndmask_b32_e64 v3, v9, v3, s[12:13]
	v_add_f32_e32 v4, v4, v2
	v_add_f32_e32 v5, v5, v3
	v_cndmask_b32_e64 v2, v2, v4, s[6:7]
	v_cndmask_b32_e64 v3, v3, v5, s[6:7]
	v_add_f32_e32 v4, v10, v2
	v_add_f32_e32 v5, v11, v3
	v_cndmask_b32_e64 v2, v2, v4, s[14:15]
	v_cndmask_b32_e64 v3, v3, v5, s[14:15]
	v_add_f32_e32 v4, v12, v2
	v_add_f32_e32 v5, v13, v3
	v_cndmask_b32_e64 v2, v2, v4, s[16:17]
	v_cndmask_b32_e64 v3, v3, v5, s[16:17]
	v_add_f32_e32 v4, v32, v2
	v_add_f32_e32 v5, v33, v3
	v_cndmask_b32_e64 v2, v2, v4, s[18:19]
	v_cndmask_b32_e64 v3, v3, v5, s[18:19]
	v_add_f32_e32 v4, v34, v2
	v_add_f32_e32 v5, v35, v3
	v_cndmask_b32_e64 v105, v2, v4, s[20:21]
	v_max_f32_e64 v2, -v150, -v150
	v_cndmask_b32_e64 v104, v3, v5, s[20:21]
	v_min_f32_e32 v2, 0x42e60000, v2
	v_exp_f32_e32 v4, v2
	v_max_f32_e64 v2, -v149, -v149
	v_add_f32_e32 v32, v88, v105
	v_add_f32_e32 v33, v89, v104
	v_min_f32_e32 v2, 0x42e60000, v2
	v_exp_f32_e32 v8, v32
	v_exp_f32_e32 v9, v33
	v_exp_f32_e32 v5, v2
	v_sub_f32_e32 v2, v150, v32
	v_min_f32_e32 v2, 0x42e60000, v2
	v_exp_f32_e32 v10, v2
	v_sub_f32_e32 v2, v149, v33
	v_sub_f32_e32 v33, v151, v33
	v_min_f32_e32 v2, 0x42e60000, v2
	v_pk_mul_f32 v[8:9], v[8:9], v[156:157]
	v_exp_f32_e32 v34, v33
	v_add_f32_e32 v33, v86, v105
	v_add_f32_e32 v35, v87, v104
	v_exp_f32_e32 v11, v2
	v_pk_mul_f32 v[12:13], v[4:5], v[8:9]
	v_cvt_pk_bf16_f32 v88, v8, v9
	v_exp_f32_e32 v8, v33
	v_exp_f32_e32 v9, v35
	v_exp_f32_e32 v103, v7
	v_lshlrev_b32_e32 v44, 16, v90
	v_and_b32_e32 v45, 0xffff0000, v90
	v_lshlrev_b32_e32 v6, 16, v91
	v_and_b32_e32 v7, 0xffff0000, v91
	v_pk_add_f32 v[90:91], v[92:93], 1.0 op_sel_hi:[1,0] neg_lo:[1,0] neg_hi:[1,0]
	v_cvt_pk_bf16_f32 v89, v12, v13
	v_pk_mul_f32 v[10:11], v[90:91], v[10:11]
	v_sub_f32_e32 v12, v150, v33
	v_sub_f32_e32 v13, v149, v35
	v_pk_mul_f32 v[8:9], v[8:9], v[158:159]
	v_pk_add_f32 v[2:3], v[102:103], 1.0 op_sel_hi:[1,0] neg_lo:[1,0] neg_hi:[1,0]
	v_min_f32_e32 v12, 0x42e60000, v12
	v_min_f32_e32 v13, 0x42e60000, v13
	v_cvt_pk_bf16_f32 v102, v10, v11
	v_pk_mul_f32 v[10:11], v[4:5], v[8:9]
	v_cvt_pk_bf16_f32 v8, v8, v9
	v_exp_f32_e32 v12, v12
	v_exp_f32_e32 v13, v13
	ds_write2_b32 v146, v88, v8 offset1:68
	v_cvt_pk_bf16_f32 v8, v10, v11
	v_add_f32_e32 v82, v82, v105
	v_add_f32_e32 v83, v83, v104
	ds_write2_b32 v153, v89, v8 offset1:68
	v_exp_f32_e32 v8, v82
	v_exp_f32_e32 v9, v83
	v_pk_add_f32 v[92:93], v[96:97], 1.0 op_sel_hi:[1,0] neg_lo:[1,0] neg_hi:[1,0]
	v_sub_f32_e32 v10, v150, v82
	v_pk_mul_f32 v[12:13], v[92:93], v[12:13]
	v_sub_f32_e32 v11, v149, v83
	v_cvt_pk_bf16_f32 v12, v12, v13
	v_add_u32_e32 v88, 0x8800, v146
	v_min_f32_e32 v10, 0x42e60000, v10
	v_min_f32_e32 v11, 0x42e60000, v11
	v_pk_mul_f32 v[8:9], v[8:9], v[160:161]
	v_add_f32_e32 v46, v46, v105
	v_add_f32_e32 v47, v47, v104
	v_exp_f32_e32 v10, v10
	v_exp_f32_e32 v11, v11
	ds_write2_b32 v88, v102, v12 offset1:68
	v_pk_mul_f32 v[12:13], v[4:5], v[8:9]
	v_cvt_pk_bf16_f32 v89, v8, v9
	v_exp_f32_e32 v8, v46
	v_exp_f32_e32 v9, v47
	v_pk_add_f32 v[94:95], v[94:95], 1.0 op_sel_hi:[1,0] neg_lo:[1,0] neg_hi:[1,0]
	v_mov_b32_e32 v86, v90
	v_pk_mul_f32 v[10:11], v[94:95], v[10:11]
	v_cvt_pk_bf16_f32 v90, v12, v13
	v_sub_f32_e32 v12, v150, v46
	v_sub_f32_e32 v13, v149, v47
	v_pk_mul_f32 v[8:9], v[8:9], v[162:163]
	v_mov_b32_e32 v87, v92
	v_mov_b32_e32 v92, v91
	v_min_f32_e32 v12, 0x42e60000, v12
	v_min_f32_e32 v13, 0x42e60000, v13
	v_cvt_pk_bf16_f32 v91, v10, v11
	v_pk_mul_f32 v[10:11], v[4:5], v[8:9]
	v_cvt_pk_bf16_f32 v8, v8, v9
	v_exp_f32_e32 v12, v12
	v_exp_f32_e32 v13, v13
	ds_write2_b32 v146, v89, v8 offset0:136 offset1:204
	v_cvt_pk_bf16_f32 v8, v10, v11
	v_add_f32_e32 v40, v40, v105
	v_add_f32_e32 v41, v41, v104
	ds_write2_b32 v153, v90, v8 offset0:136 offset1:204
	v_exp_f32_e32 v8, v40
	v_exp_f32_e32 v9, v41
	v_pk_add_f32 v[96:97], v[98:99], 1.0 op_sel_hi:[1,0] neg_lo:[1,0] neg_hi:[1,0]
	v_lshlrev_b32_e32 v164, 16, v84
	v_and_b32_e32 v165, 0xffff0000, v84
	v_pk_mul_f32 v[12:13], v[96:97], v[12:13]
	v_sub_f32_e32 v10, v150, v40
	v_sub_f32_e32 v11, v149, v41
	v_cvt_pk_bf16_f32 v12, v12, v13
	v_min_f32_e32 v10, 0x42e60000, v10
	v_min_f32_e32 v11, 0x42e60000, v11
; #define LAS __attribute__((address_space(3)))
; #define MFMA32(a, b, c) __builtin_amdgcn_mfma_f32_32x32x16_bf16((a), (b), (c), 0, 0, 0)
; __device__ __forceinline__ unsigned pk2(float lo, float hi) { f32x2_t v = {lo, hi}; bf16x2_t b = __builtin_convertvector(v, bf16x2_t); return __builtin_bit_cast(unsigned, b); }
; __device__ __forceinline__ void scan_item(const Ctx& C, int b, int h, int half, const bf16* HQ, const bf16* LOGF, bf16* HI  , float* SSQ) {
;     ...
;           for (int i = 0; i < 8; ++i) { const int t = 8 * w + i; const float b0 = pre0 + c0[i], b1 = pre1 + c1[i];
;               const float e0 = __builtin_amdgcn_exp2f(b0), e1 = __builtin_amdgcn_exp2f(b1);
;               const float qd0 = q0[i] * e0, qd1 = q1[i] * e1, qt0 = qd0 * cm0, qt1 = qd1 * cm1;
;               const float kt0 = kk0[i] * __builtin_amdgcn_exp2f(fminf(mid0 - b0, 115.f)), kt1 = kk1[i] * __builtin_amdgcn_exp2f(fminf(mid1 - b1, 115.f));
;               kd0[i] = kk0[i] * __builtin_amdgcn_exp2f(tot0 - b0); kd1[i] = kk1[i] * __builtin_amdgcn_exp2f(tot1 - b1);
;               *(LAS unsigned*)(L + O_QD + (t * P128 + k0) * 2) = pk2(qd0, qd1); *(LAS unsigned*)(L + O_QT + (t * P128 + k0) * 2) = pk2(qt0, qt1); *(LAS unsigned*)(L + O_KT + (t * P128 + k0) * 2) = pk2(kt0, kt1); }
;           *(LAS v4u*)(L + O_KDT + (k0 * P64 + 8 * w) * 2) = (v4u){pk2(kd0[0], kd0[1]), pk2(kd0[2], kd0[3]), pk2(kd0[4], kd0[5]), pk2(kd0[6], kd0[7])};
;           *(LAS v4u*)(L + O_KDT + ((k0 + 1) * P64 + 8 * w) * 2) = (v4u){pk2(kd1[0], kd1[1]), pk2(kd1[2], kd1[3]), pk2(kd1[4], kd1[5]), pk2(kd1[6], kd1[7])}; }
;         __syncthreads();
;     ...
; #pragma unroll
;             for (int s = 0; s < 8; ++s) { const bf16x8 a = *(const LAS bf16x8*)(L + O_QD + ((32 * ti + r) * P128 + 16 * s + 8 * hh) * 2), bb = *(const LAS bf16x8*)(L + O_ST + ((32 * xi + r) * P128 + 16 * s + 8 * hh) * 2); acc = MFMA32(a, bb, acc); }
;         }
	v_pk_mul_f32 v[8:9], v[8:9], v[164:165]
	v_add_f32_e32 v38, v38, v105
	v_add_f32_e32 v39, v39, v104
	v_sub_f32_e32 v32, v152, v32
	v_sub_f32_e32 v33, v152, v33
	v_exp_f32_e32 v10, v10
	v_exp_f32_e32 v11, v11
	ds_write2_b32 v88, v91, v12 offset0:136 offset1:204
	v_pk_mul_f32 v[12:13], v[4:5], v[8:9]
	v_cvt_pk_bf16_f32 v88, v8, v9
	v_exp_f32_e32 v8, v38
	v_exp_f32_e32 v9, v39
	v_exp_f32_e32 v32, v32
	v_exp_f32_e32 v33, v33
	v_lshlrev_b32_e32 v84, 16, v85
	v_and_b32_e32 v85, 0xffff0000, v85
	v_pk_add_f32 v[98:99], v[100:101], 1.0 op_sel_hi:[1,0] neg_lo:[1,0] neg_hi:[1,0]
	v_sub_f32_e32 v82, v152, v82
	v_sub_f32_e32 v83, v151, v83
	v_sub_f32_e32 v46, v152, v46
	v_sub_f32_e32 v47, v151, v47
	v_pk_mul_f32 v[10:11], v[98:99], v[10:11]
	v_cvt_pk_bf16_f32 v89, v12, v13
	v_sub_f32_e32 v12, v150, v38
	v_sub_f32_e32 v13, v149, v39
	v_pk_mul_f32 v[8:9], v[8:9], v[84:85]
	v_pk_mul_f32 v[32:33], v[86:87], v[32:33]
	v_exp_f32_e32 v82, v82
	v_exp_f32_e32 v86, v83
	v_exp_f32_e32 v83, v46
	v_exp_f32_e32 v87, v47
	v_min_f32_e32 v12, 0x42e60000, v12
	v_min_f32_e32 v13, 0x42e60000, v13
	v_cvt_pk_bf16_f32 v90, v10, v11
	v_pk_mul_f32 v[10:11], v[4:5], v[8:9]
	v_cvt_pk_bf16_f32 v8, v8, v9
	v_exp_f32_e32 v12, v12
	v_exp_f32_e32 v13, v13
	ds_write2_b32 v148, v88, v8 offset0:16 offset1:84
	v_cvt_pk_bf16_f32 v8, v10, v11
	v_add_f32_e32 v36, v36, v105
	v_add_f32_e32 v37, v37, v104
	ds_write2_b32 v1, v89, v8 offset0:16 offset1:84
	v_exp_f32_e32 v8, v36
	v_exp_f32_e32 v9, v37
	v_mov_b32_e32 v46, v94
	v_mov_b32_e32 v47, v96
	v_mov_b32_e32 v96, v95
	v_sub_f32_e32 v40, v152, v40
	v_sub_f32_e32 v41, v151, v41
	v_sub_f32_e32 v38, v152, v38
	v_sub_f32_e32 v39, v151, v39
	v_sub_f32_e32 v10, v150, v36
	v_sub_f32_e32 v11, v149, v37
	v_pk_add_f32 v[100:101], v[106:107], 1.0 op_sel_hi:[1,0] neg_lo:[1,0] neg_hi:[1,0]
	v_pk_mul_f32 v[46:47], v[46:47], v[82:83]
	v_pk_mul_f32 v[82:83], v[96:97], v[86:87]
	v_exp_f32_e32 v40, v40
	v_exp_f32_e32 v86, v41
	v_exp_f32_e32 v41, v38
	v_exp_f32_e32 v87, v39
	v_min_f32_e32 v10, 0x42e60000, v10
	v_min_f32_e32 v11, 0x42e60000, v11
	v_pk_mul_f32 v[12:13], v[100:101], v[12:13]
	v_exp_f32_e32 v10, v10
	v_exp_f32_e32 v11, v11
	v_cvt_pk_bf16_f32 v12, v12, v13
	v_add_u32_e32 v84, 0x8c00, v146
	v_pk_mul_f32 v[8:9], v[8:9], v[44:45]
	v_mov_b32_e32 v38, v98
	v_mov_b32_e32 v39, v100
	v_mov_b32_e32 v100, v99
	ds_write2_b32 v84, v90, v12 offset0:16 offset1:84
	v_pk_mul_f32 v[12:13], v[4:5], v[8:9]
	v_add_f32_e32 v14, v14, v105
	v_add_f32_e32 v15, v15, v104
	v_pk_mul_f32 v[38:39], v[38:39], v[40:41]
	v_pk_mul_f32 v[40:41], v[100:101], v[86:87]
	v_cvt_pk_bf16_f32 v86, v12, v13
	v_sub_f32_e32 v12, v150, v14
	v_sub_f32_e32 v13, v149, v15
	v_pk_mul_f32 v[10:11], v[42:43], v[10:11]
	v_min_f32_e32 v12, 0x42e60000, v12
	v_min_f32_e32 v13, 0x42e60000, v13
	v_sub_f32_e32 v37, v151, v37
	v_cvt_pk_bf16_f32 v85, v8, v9
	v_exp_f32_e32 v8, v14
	v_exp_f32_e32 v9, v15
	v_exp_f32_e32 v12, v12
	v_exp_f32_e32 v13, v13
	v_cvt_pk_bf16_f32 v87, v10, v11
	v_sub_f32_e32 v11, v151, v15
	v_exp_f32_e32 v44, v37
	v_exp_f32_e32 v45, v11
	v_sub_f32_e32 v36, v152, v36
	v_sub_f32_e32 v10, v152, v14
	v_sub_f32_e32 v35, v151, v35
	v_exp_f32_e32 v36, v36
	v_exp_f32_e32 v37, v10
	v_exp_f32_e32 v35, v35
	v_pk_mul_f32 v[6:7], v[8:9], v[6:7]
	v_pk_mul_f32 v[8:9], v[2:3], v[12:13]
	v_mov_b32_e32 v11, v2
	v_mov_b32_e32 v2, v43
	v_pk_mul_f32 v[4:5], v[4:5], v[6:7]
	v_pk_mul_f32 v[12:13], v[2:3], v[44:45]
	v_cvt_pk_bf16_f32 v2, v6, v7
	v_mov_b32_e32 v10, v42
	ds_write2_b32 v148, v85, v2 offset0:152 offset1:220
	v_cvt_pk_bf16_f32 v2, v4, v5
	v_pk_mul_f32 v[10:11], v[10:11], v[36:37]
	ds_write2_b32 v1, v86, v2 offset0:152 offset1:220
	v_cvt_pk_bf16_f32 v1, v8, v9
	v_pk_mul_f32 v[34:35], v[92:93], v[34:35]
	ds_write2_b32 v84, v87, v1 offset0:152 offset1:220
	v_cvt_pk_bf16_f32 v2, v32, v33
	v_cvt_pk_bf16_f32 v3, v46, v47
	v_cvt_pk_bf16_f32 v4, v38, v39
	v_cvt_pk_bf16_f32 v5, v10, v11
	v_cndmask_b32_e64 v1, 0, 1, s[6:7]
	ds_write_b128 v142, v[2:5]
	v_cvt_pk_bf16_f32 v2, v34, v35
	v_cvt_pk_bf16_f32 v3, v82, v83
	v_cvt_pk_bf16_f32 v4, v40, v41
	v_cvt_pk_bf16_f32 v5, v12, v13
	v_cmp_ne_u32_e64 s[56:57], 1, v1
	s_andn2_b64 vcc, exec, s[6:7]
	s_mov_b64 s[96:97], -1
	ds_write_b128 v142, v[2:5] offset:144
	s_waitcnt lgkmcnt(0)
	s_barrier
	s_cbranch_vccnz .LBB0_718
	v_add_u32_e32 v1, 0, v114
	v_add_u32_e32 v10, 0, v115
	ds_read_b128 v[2:5], v1
	ds_read_b128 v[6:9], v10 offset:52224
	ds_read_b128 v[166:169], v1 offset:32
	ds_read_b128 v[170:173], v10 offset:52256
	ds_read_b128 v[174:177], v1 offset:64
	ds_read_b128 v[178:181], v10 offset:52288
	ds_read_b128 v[182:185], v1 offset:96
	ds_read_b128 v[186:189], v10 offset:52320
	ds_read_b128 v[194:197], v1 offset:128
	ds_read_b128 v[198:201], v10 offset:52352
	ds_read_b128 v[202:205], v1 offset:160
	ds_read_b128 v[206:209], v10 offset:52384
	s_mov_b64 s[96:97], 0
	s_waitcnt lgkmcnt(10)
	v_mfma_f32_32x32x16_bf16 v[32:47], v[2:5], v[6:9], 0
	ds_read_b128 v[210:213], v1 offset:192
	ds_read_b128 v[214:217], v10 offset:52416
	s_waitcnt lgkmcnt(10)
	v_mfma_f32_32x32x16_bf16 v[32:47], v[166:169], v[170:173], v[32:47]
	ds_read_b128 v[218:221], v1 offset:224
	ds_read_b128 v[222:225], v10 offset:52448
	s_waitcnt lgkmcnt(10)
	v_mfma_f32_32x32x16_bf16 v[32:47], v[174:177], v[178:181], v[32:47]
	s_waitcnt lgkmcnt(8)
	v_mfma_f32_32x32x16_bf16 v[32:47], v[182:185], v[186:189], v[32:47]
	s_waitcnt lgkmcnt(6)
	v_mfma_f32_32x32x16_bf16 v[32:47], v[194:197], v[198:201], v[32:47]
	s_waitcnt lgkmcnt(4)
	v_mfma_f32_32x32x16_bf16 v[32:47], v[202:205], v[206:209], v[32:47]
	s_waitcnt lgkmcnt(2)
	v_mfma_f32_32x32x16_bf16 v[32:47], v[210:213], v[214:217], v[32:47]
	s_waitcnt lgkmcnt(0)
	v_mfma_f32_32x32x16_bf16 v[32:47], v[218:221], v[222:225], v[32:47]
; #define LAS __attribute__((address_space(3)))
; #define MFMA32(a, b, c) __builtin_amdgcn_mfma_f32_32x32x16_bf16((a), (b), (c), 0, 0, 0)
; __device__ __forceinline__ void scan_item(const Ctx& C, int b, int h, int half, const bf16* HQ, const bf16* LOGF, bf16* HI  , float* SSQ) {
;     ...
;         if (w < 4) {
;             if (xi <= ti) {
; #pragma unroll
;                 for (int s = 0; s < 8; ++s) { const bf16x8 a = *(const LAS bf16x8*)(L + O_QT + ((32 * ti + r) * P128 + 16 * s + 8 * hh) * 2), bb = *(const LAS bf16x8*)(L + O_KT + ((32 * xi + r) * P128 + 16 * s + 8 * hh) * 2); acc = MFMA32(a, bb, acc); }
;             }
.LBB0_718:
	s_andn2_b64 vcc, exec, s[96:97]
	s_cbranch_vccnz .LBB0_723
	s_andn2_b64 vcc, exec, s[94:95]
	s_cbranch_vccnz .LBB0_721
	v_add_u32_e32 v1, 0, v114
	v_add_u32_e32 v10, 0, v115
	ds_read_b128 v[2:5], v1 offset:17408
	ds_read_b128 v[6:9], v10 offset:34816
	ds_read_b128 v[166:169], v1 offset:17440
	ds_read_b128 v[170:173], v10 offset:34848
	ds_read_b128 v[174:177], v1 offset:17472
	ds_read_b128 v[178:181], v10 offset:34880
	ds_read_b128 v[182:185], v1 offset:17504
	ds_read_b128 v[186:189], v10 offset:34912
	ds_read_b128 v[194:197], v1 offset:17536
	ds_read_b128 v[198:201], v10 offset:34944
	ds_read_b128 v[202:205], v1 offset:17568
	ds_read_b128 v[206:209], v10 offset:34976
	s_waitcnt lgkmcnt(10)
	v_mfma_f32_32x32x16_bf16 v[32:47], v[2:5], v[6:9], 0
	ds_read_b128 v[210:213], v1 offset:17600
	ds_read_b128 v[214:217], v10 offset:35008
	s_waitcnt lgkmcnt(10)
	v_mfma_f32_32x32x16_bf16 v[32:47], v[166:169], v[170:173], v[32:47]
	ds_read_b128 v[218:221], v1 offset:17632
	ds_read_b128 v[222:225], v10 offset:35040
	s_waitcnt lgkmcnt(10)
	v_mfma_f32_32x32x16_bf16 v[32:47], v[174:177], v[178:181], v[32:47]
	s_waitcnt lgkmcnt(8)
	v_mfma_f32_32x32x16_bf16 v[32:47], v[182:185], v[186:189], v[32:47]
	s_waitcnt lgkmcnt(6)
	v_mfma_f32_32x32x16_bf16 v[32:47], v[194:197], v[198:201], v[32:47]
	s_waitcnt lgkmcnt(4)
	v_mfma_f32_32x32x16_bf16 v[32:47], v[202:205], v[206:209], v[32:47]
	s_waitcnt lgkmcnt(2)
	v_mfma_f32_32x32x16_bf16 v[32:47], v[210:213], v[214:217], v[32:47]
	s_waitcnt lgkmcnt(0)
	v_mfma_f32_32x32x16_bf16 v[32:47], v[218:221], v[222:225], v[32:47]
	s_branch .LBB0_722

; #define LAS __attribute__((address_space(3)))
; #define MFMA32(a, b, c) __builtin_amdgcn_mfma_f32_32x32x16_bf16((a), (b), (c), 0, 0, 0)
; __device__ __forceinline__ unsigned f2bf(float f) { unsigned u = __builtin_bit_cast(unsigned, f); return (u + 0x7fffu + ((u >> 16) & 1u)) >> 16; }
; __device__ __forceinline__ void scan_item(const Ctx& C, int b, int h, int half, const bf16* HQ, const bf16* LOGF, bf16* HI  , float* SSQ) {
;     ...
;         if (w >= 4) {
; #pragma unroll
;             for (int s = 0; s < 4; ++s) { const bf16x8 a = *(const LAS bf16x8*)(L + O_SC + ((32 * ti + r) * P64 + 16 * s + 8 * hh) * 2), bb = *(const LAS bf16x8*)(L + O_VT + ((32 * xi + r) * P64 + 16 * s + 8 * hh) * 2); acc = MFMA32(a, bb, acc); }
; #pragma unroll
;             for (int i = 0; i < 16; ++i) { const int t = 32 * ti + (i & 3) + 8 * (i >> 2) + 4 * hh; *(LAS bf16*)(L + O_OT + (t * P64 + 32 * xi + r) * 2) = (bf16)f2bf(acc[i]); }
;         }
.LBB0_723:
	s_and_b64 vcc, exec, s[56:57]
	v_add_u32_e32 v1, 0x15800, v147
	s_waitcnt lgkmcnt(0)
	s_barrier
	s_cbranch_vccnz .LBB0_707
	ds_read_b128 v[2:5], v143
	ds_read_b128 v[6:9], v143 offset:32
	ds_read_b128 v[10:13], v1
	ds_read_b128 v[82:85], v1 offset:32
	ds_read_b128 v[166:169], v143 offset:64
	ds_read_b128 v[170:173], v1 offset:64
	ds_read_b128 v[174:177], v143 offset:96
	ds_read_b128 v[178:181], v1 offset:96
	s_add_i32 s56, 0, 0x1b200
	s_waitcnt lgkmcnt(5)
	v_mfma_f32_32x32x16_bf16 v[32:47], v[2:5], v[10:13], v[32:47]
	s_waitcnt lgkmcnt(4)
	v_mfma_f32_32x32x16_bf16 v[32:47], v[6:9], v[82:85], v[32:47]
	s_waitcnt lgkmcnt(2)
	v_mfma_f32_32x32x16_bf16 v[32:47], v[166:169], v[170:173], v[32:47]
	s_waitcnt lgkmcnt(0)
	v_mfma_f32_32x32x16_bf16 v[32:47], v[174:177], v[178:181], v[32:47]
	v_add_u32_e32 v3, s56, v116
	s_nop 10
	v_bfe_u32 v2, v32, 16, 1
	v_add3_u32 v2, v32, v2, s75
	ds_write_b16_d16_hi v3, v2
	v_bfe_u32 v2, v33, 16, 1
	v_add3_u32 v2, v33, v2, s75
	v_add_u32_e32 v3, s56, v117
	ds_write_b16_d16_hi v3, v2
	v_bfe_u32 v2, v34, 16, 1
	v_add3_u32 v2, v34, v2, s75
	v_add_u32_e32 v3, s56, v118
	ds_write_b16_d16_hi v3, v2
	v_bfe_u32 v2, v35, 16, 1
	v_add3_u32 v2, v35, v2, s75
	v_add_u32_e32 v3, s56, v119
	ds_write_b16_d16_hi v3, v2
	v_bfe_u32 v2, v36, 16, 1
	v_add3_u32 v2, v36, v2, s75
	v_add_u32_e32 v3, s56, v120
	ds_write_b16_d16_hi v3, v2
	v_bfe_u32 v2, v37, 16, 1
	v_add3_u32 v2, v37, v2, s75
	v_add_u32_e32 v3, s56, v121
	ds_write_b16_d16_hi v3, v2
	v_bfe_u32 v2, v38, 16, 1
	v_add3_u32 v2, v38, v2, s75
	v_add_u32_e32 v3, s56, v122
	ds_write_b16_d16_hi v3, v2
	v_bfe_u32 v2, v39, 16, 1
	v_add3_u32 v2, v39, v2, s75
	v_add_u32_e32 v3, s56, v123
	ds_write_b16_d16_hi v3, v2
	v_bfe_u32 v2, v40, 16, 1
	v_add3_u32 v2, v40, v2, s75
	v_add_u32_e32 v3, s56, v124
	ds_write_b16_d16_hi v3, v2
	v_bfe_u32 v2, v41, 16, 1
	v_add3_u32 v2, v41, v2, s75
	v_add_u32_e32 v3, s56, v125
	ds_write_b16_d16_hi v3, v2
	v_bfe_u32 v2, v42, 16, 1
	v_add3_u32 v2, v42, v2, s75
	v_add_u32_e32 v3, s56, v126
	ds_write_b16_d16_hi v3, v2
	v_bfe_u32 v2, v43, 16, 1
	v_add3_u32 v2, v43, v2, s75
	v_add_u32_e32 v3, s56, v127
	ds_write_b16_d16_hi v3, v2
	v_bfe_u32 v2, v44, 16, 1
	v_add3_u32 v2, v44, v2, s75
	v_add_u32_e32 v3, s56, v128
	ds_write_b16_d16_hi v3, v2
	v_bfe_u32 v2, v45, 16, 1
	v_add3_u32 v2, v45, v2, s75
	v_add_u32_e32 v3, s56, v129
	ds_write_b16_d16_hi v3, v2
	v_bfe_u32 v2, v46, 16, 1
	v_add3_u32 v2, v46, v2, s75
	v_add_u32_e32 v3, s56, v130
	ds_write_b16_d16_hi v3, v2
	v_bfe_u32 v2, v47, 16, 1
	v_add3_u32 v2, v47, v2, s75
	v_add_u32_e32 v3, s56, v131
	ds_write_b16_d16_hi v3, v2
	s_branch .LBB0_707
